# fold_tiles (latent part): XOR-swizzled 16-byte chunks in the LDS transpose image (ds_write_b16 bank conflicts); on top of v16
# baseline (speedup 1.0000x reference)
; #define LAS __attribute__((address_space(3)))
; #define GAS __attribute__((address_space(1)))
; DI unsigned pk2(float lo, float hi) { f32x2_t v = {lo, hi}; bf16x2_t b = __builtin_convertvector(v, bf16x2_t); return __builtin_bit_cast(unsigned, b); }
; DI void fold_tiles(const Ctx& C, const GAS bf16* PQ, int rowbase, int L, GAS bf16* Bt, bool jf) {
;     LAS bf16* sm = (LAS bf16*)C.lds;
;     const int nkb = L / 64, ntiles = 8 * nkb, half = L / 2;
;     const int rl = C.tid >> 3, c8 = C.tid & 7;
;     for (int tile = C.blk; tile < ntiles; tile += C.G) {
;         const int nb = tile / nkb, kb = tile % nkb, n0 = nb * 256, b = n0 >> 9, ch0 = n0 & 511, kk = kb * 64 + rl;
;         int colb, l1, l2; bool has2; float sg, sa = 1.f;
;     ...
;             for (int i = 0; i < 8; ++i) sm[(64 * q + 8 * c8 + i) * 72 + rl] = (bf16)(pk2(f[i], 0.f) & 0xffff);
;         }
;         __syncthreads();
; #pragma unroll
;         for (int q = 0; q < 4; ++q) { const u32x4 o = *(const LAS u32x4*)(sm + (64 * q + rl) * 72 + 8 * c8);
.LBB0_581:
	s_cmp_lt_i32 s78, 8
	s_cselect_b64 s[0:1], -1, 0
	s_cmp_gt_i32 s79, 7
	s_cselect_b64 s[2:3], -1, 0
	s_and_b64 s[0:1], s[0:1], s[2:3]
	s_andn2_b64 vcc, exec, s[0:1]
	s_cbranch_vccnz .LBB0_673
	s_mov_b32 s23, 0
	s_waitcnt vmcnt(3)
	v_mov_b32_e32 v2, v1
	s_mov_b32 s2, s63
	s_mov_b64 s[6:7], s[74:75]
	s_mov_b32 s4, s62
	s_mov_b64 s[0:1], s[34:35]
	s_add_i32 s22, s23, 0
	s_add_u32 s6, s0, 0xe400000
	s_addc_u32 s7, s1, 0
	v_ashrrev_i32_e32 v3, 3, v2
	v_readfirstlane_b32 s3, v2
	s_cmpk_gt_i32 s2, 0x3ff
	s_waitcnt vmcnt(1)
	v_lshlrev_b32_e32 v11, 3, v2
	v_lshl_add_u32 v10, v3, 1, s22
	s_cbranch_scc1 .LBB0_589
	v_and_b32_e32 v8, 56, v11
	v_mov_b32_e32 v5, 0
	v_lshlrev_b32_e32 v4, 1, v8
	s_movk_i32 s5, 0x90
	v_add_u32_e32 v13, s22, v4
	v_lshl_add_u64 v[6:7], s[0:1], 0, v[4:5]
	s_mov_b64 s[8:9], 0x14700000
	v_mul_lo_u32 v4, v3, s5
	v_mul_u32_u24_e32 v12, 0x90, v8
	v_lshl_add_u64 v[6:7], v[6:7], 0, s[8:9]
	s_lshl_b32 s5, s2, 6
	s_lshl_b32 s12, s4, 6
	s_movk_i32 s13, 0xfff
	v_lshlrev_b32_e32 v8, 1, v8
	v_mov_b32_e32 v9, v5
	v_add_u32_e32 v12, v10, v12
	v_add_u32_e32 v13, v13, v4
	v_lshrrev_b32_e32 v14, 3, v3
	v_lshrrev_b32_e32 v15, 4, v8
	v_xor_b32_e32 v16, v14, v15
	v_sub_u32_e32 v14, v16, v14
	v_lshl_add_u32 v12, v14, 4, v12
	v_sub_u32_e32 v15, v16, v15
	v_lshl_add_u32 v13, v15, 4, v13
	s_mov_b32 s24, s2
	s_branch .LBB0_585
